# EpiUp software-pipelined across blocks (trans ops of block b interleaved with conv fmacs of block b+1)
# speedup vs baseline: 1.0152x; 1.0081x over previous
.Lepi_nohr:
	s_waitcnt lgkmcnt(0)
	s_barrier
	v_cmp_eq_u32_e32 vcc, 0, v177
	v_cndmask_b32_e64 v182, 0, v14, s[42:43]
	v_cndmask_b32_e64 v183, 0, v15, s[42:43]
	v_cndmask_b32_e64 v184, 0, v16, s[42:43]
	v_cndmask_b32_e64 v185, 0, v17, s[42:43]
	v_cndmask_b32_e64 v190, 0, v22, s[42:43]
	v_cndmask_b32_e64 v191, 0, v23, s[42:43]
	v_cndmask_b32_e64 v192, 0, v24, s[42:43]
	v_cndmask_b32_e64 v193, 0, v25, s[42:43]
	v_cndmask_b32_e32 v154, 0, v26, vcc
	v_cndmask_b32_e32 v155, 0, v27, vcc
	v_cndmask_b32_e32 v156, 0, v28, vcc
	v_cndmask_b32_e32 v157, 0, v29, vcc
	v_cndmask_b32_e32 v158, 0, v74, vcc
	v_cndmask_b32_e32 v159, 0, v75, vcc
	v_cndmask_b32_e32 v160, 0, v76, vcc
	v_cndmask_b32_e32 v161, 0, v77, vcc
	v_mov_b64_e32 v[194:195], 0
	v_mov_b64_e32 v[196:197], 0
	v_mov_b64_e32 v[198:199], 0
	v_mov_b64_e32 v[200:201], 0
	v_mov_b64_e32 v[210:211], 0
	v_mov_b64_e32 v[212:213], 0
	v_mov_b64_e32 v[214:215], 0
	v_mov_b64_e32 v[216:217], 0
	s_cmp_lt_i32 s15, 1
	s_cbranch_scc1 .Lepi_gp0
	s_and_saveexec_b64 s[70:71], s[40:41]
	ds_read_b128 v[194:197], v187
	ds_read_b128 v[198:201], v187 offset:16
	s_or_b64 exec, exec, s[70:71]
.Lepi_gp0:
	s_and_saveexec_b64 s[70:71], s[40:41]
	ds_read_b128 v[210:213], v187 offset:2048
	ds_read_b128 v[214:217], v187 offset:2064
	s_or_b64 exec, exec, s[70:71]
	s_waitcnt lgkmcnt(0)
	v_pk_mul_f32 v[202:203], v[150:151], v[78:79]
	v_pk_mul_f32 v[204:205], v[152:153], v[80:81]
	v_pk_mul_f32 v[206:207], v[58:59], v[82:83]
	v_pk_mul_f32 v[226:227], v[60:61], v[84:85]
	v_fmac_f32_dpp v202, v150, v26 row_shr:1 row_mask:0xf bank_mask:0xf bound_ctrl:1
	v_fmac_f32_dpp v203, v151, v27 row_shr:1 row_mask:0xf bank_mask:0xf bound_ctrl:1
	v_fmac_f32_dpp v204, v152, v28 row_shr:1 row_mask:0xf bank_mask:0xf bound_ctrl:1
	v_fmac_f32_dpp v205, v153, v29 row_shr:1 row_mask:0xf bank_mask:0xf bound_ctrl:1
	v_fmac_f32_dpp v206, v58, v74 row_shr:1 row_mask:0xf bank_mask:0xf bound_ctrl:1
	v_fmac_f32_dpp v207, v59, v75 row_shr:1 row_mask:0xf bank_mask:0xf bound_ctrl:1
	v_fmac_f32_dpp v226, v60, v76 row_shr:1 row_mask:0xf bank_mask:0xf bound_ctrl:1
	v_fmac_f32_dpp v227, v61, v77 row_shr:1 row_mask:0xf bank_mask:0xf bound_ctrl:1
	v_fmac_f32_dpp v202, v150, v14 row_shr:2 row_mask:0xf bank_mask:0xf bound_ctrl:1
	v_fmac_f32_dpp v203, v151, v15 row_shr:2 row_mask:0xf bank_mask:0xf bound_ctrl:1
	v_fmac_f32_dpp v204, v152, v16 row_shr:2 row_mask:0xf bank_mask:0xf bound_ctrl:1
	v_fmac_f32_dpp v205, v153, v17 row_shr:2 row_mask:0xf bank_mask:0xf bound_ctrl:1
	v_fmac_f32_dpp v206, v58, v22 row_shr:2 row_mask:0xf bank_mask:0xf bound_ctrl:1
	v_fmac_f32_dpp v207, v59, v23 row_shr:2 row_mask:0xf bank_mask:0xf bound_ctrl:1
	v_fmac_f32_dpp v226, v60, v24 row_shr:2 row_mask:0xf bank_mask:0xf bound_ctrl:1
	v_fmac_f32_dpp v227, v61, v25 row_shr:2 row_mask:0xf bank_mask:0xf bound_ctrl:1
	v_fmac_f32_dpp v202, v194, v154 row_ror:1 row_mask:0xf bank_mask:0xf bound_ctrl:1
	v_fmac_f32_dpp v203, v195, v155 row_ror:1 row_mask:0xf bank_mask:0xf bound_ctrl:1
	v_fmac_f32_dpp v204, v196, v156 row_ror:1 row_mask:0xf bank_mask:0xf bound_ctrl:1
	v_fmac_f32_dpp v205, v197, v157 row_ror:1 row_mask:0xf bank_mask:0xf bound_ctrl:1
	v_fmac_f32_dpp v206, v198, v158 row_ror:1 row_mask:0xf bank_mask:0xf bound_ctrl:1
	v_fmac_f32_dpp v207, v199, v159 row_ror:1 row_mask:0xf bank_mask:0xf bound_ctrl:1
	v_fmac_f32_dpp v226, v200, v160 row_ror:1 row_mask:0xf bank_mask:0xf bound_ctrl:1
	v_fmac_f32_dpp v227, v201, v161 row_ror:1 row_mask:0xf bank_mask:0xf bound_ctrl:1
	v_fmac_f32_dpp v202, v194, v182 row_ror:2 row_mask:0xf bank_mask:0xf bound_ctrl:1
	v_fmac_f32_dpp v203, v195, v183 row_ror:2 row_mask:0xf bank_mask:0xf bound_ctrl:1
	v_fmac_f32_dpp v204, v196, v184 row_ror:2 row_mask:0xf bank_mask:0xf bound_ctrl:1
	v_fmac_f32_dpp v205, v197, v185 row_ror:2 row_mask:0xf bank_mask:0xf bound_ctrl:1
	v_fmac_f32_dpp v206, v198, v190 row_ror:2 row_mask:0xf bank_mask:0xf bound_ctrl:1
	v_fmac_f32_dpp v207, v199, v191 row_ror:2 row_mask:0xf bank_mask:0xf bound_ctrl:1
	v_fmac_f32_dpp v226, v200, v192 row_ror:2 row_mask:0xf bank_mask:0xf bound_ctrl:1
	v_fmac_f32_dpp v227, v201, v193 row_ror:2 row_mask:0xf bank_mask:0xf bound_ctrl:1
	s_mov_b64 s[72:73], s[84:85]
	v_pk_mul_f32 v[218:219], v[126:127], v[78:79]
	v_pk_mul_f32 v[242:243], v[202:203], s[98:99]
	v_pk_mul_f32 v[220:221], v[128:129], v[80:81]
	v_pk_mul_f32 v[244:245], v[204:205], s[98:99]
	v_pk_mul_f32 v[222:223], v[122:123], v[82:83]
	v_pk_mul_f32 v[246:247], v[206:207], s[98:99]
	v_pk_mul_f32 v[224:225], v[124:125], v[84:85]
	v_pk_mul_f32 v[248:249], v[226:227], s[98:99]
	v_fmac_f32_dpp v218, v126, v26 row_shr:1 row_mask:0xf bank_mask:0xf bound_ctrl:1
	v_exp_f32_e32 v242, v242
	v_fmac_f32_dpp v219, v127, v27 row_shr:1 row_mask:0xf bank_mask:0xf bound_ctrl:1
	v_exp_f32_e32 v243, v243
	v_fmac_f32_dpp v220, v128, v28 row_shr:1 row_mask:0xf bank_mask:0xf bound_ctrl:1
	v_exp_f32_e32 v244, v244
	v_fmac_f32_dpp v221, v129, v29 row_shr:1 row_mask:0xf bank_mask:0xf bound_ctrl:1
	v_exp_f32_e32 v245, v245
	v_fmac_f32_dpp v222, v122, v74 row_shr:1 row_mask:0xf bank_mask:0xf bound_ctrl:1
	v_exp_f32_e32 v246, v246
	v_fmac_f32_dpp v223, v123, v75 row_shr:1 row_mask:0xf bank_mask:0xf bound_ctrl:1
	v_exp_f32_e32 v247, v247
	v_fmac_f32_dpp v224, v124, v76 row_shr:1 row_mask:0xf bank_mask:0xf bound_ctrl:1
	v_exp_f32_e32 v248, v248
	v_fmac_f32_dpp v225, v125, v77 row_shr:1 row_mask:0xf bank_mask:0xf bound_ctrl:1
	v_exp_f32_e32 v249, v249
	v_fmac_f32_dpp v218, v126, v14 row_shr:2 row_mask:0xf bank_mask:0xf bound_ctrl:1
	v_pk_add_f32 v[242:243], v[242:243], s[92:93]
	v_fmac_f32_dpp v219, v127, v15 row_shr:2 row_mask:0xf bank_mask:0xf bound_ctrl:1
	v_pk_add_f32 v[244:245], v[244:245], s[92:93]
	v_fmac_f32_dpp v220, v128, v16 row_shr:2 row_mask:0xf bank_mask:0xf bound_ctrl:1
	v_pk_add_f32 v[246:247], v[246:247], s[92:93]
	v_fmac_f32_dpp v221, v129, v17 row_shr:2 row_mask:0xf bank_mask:0xf bound_ctrl:1
	v_pk_add_f32 v[248:249], v[248:249], s[92:93]
	v_fmac_f32_dpp v222, v122, v22 row_shr:2 row_mask:0xf bank_mask:0xf bound_ctrl:1
	v_rcp_f32_e32 v242, v242
	v_fmac_f32_dpp v223, v123, v23 row_shr:2 row_mask:0xf bank_mask:0xf bound_ctrl:1
	v_rcp_f32_e32 v243, v243
	v_fmac_f32_dpp v224, v124, v24 row_shr:2 row_mask:0xf bank_mask:0xf bound_ctrl:1
	v_rcp_f32_e32 v244, v244
	v_fmac_f32_dpp v225, v125, v25 row_shr:2 row_mask:0xf bank_mask:0xf bound_ctrl:1
	v_rcp_f32_e32 v245, v245
	v_fmac_f32_dpp v218, v150, v154 row_ror:1 row_mask:0xf bank_mask:0xf bound_ctrl:1
	v_rcp_f32_e32 v246, v246
	v_fmac_f32_dpp v219, v151, v155 row_ror:1 row_mask:0xf bank_mask:0xf bound_ctrl:1
	v_rcp_f32_e32 v247, v247
	v_fmac_f32_dpp v220, v152, v156 row_ror:1 row_mask:0xf bank_mask:0xf bound_ctrl:1
	v_rcp_f32_e32 v248, v248
	v_fmac_f32_dpp v221, v153, v157 row_ror:1 row_mask:0xf bank_mask:0xf bound_ctrl:1
	v_rcp_f32_e32 v249, v249
	v_fmac_f32_dpp v222, v58, v158 row_ror:1 row_mask:0xf bank_mask:0xf bound_ctrl:1
	v_pk_mul_f32 v[202:203], v[202:203], v[242:243]
	v_fmac_f32_dpp v223, v59, v159 row_ror:1 row_mask:0xf bank_mask:0xf bound_ctrl:1
	v_pk_mul_f32 v[204:205], v[204:205], v[244:245]
	v_fmac_f32_dpp v224, v60, v160 row_ror:1 row_mask:0xf bank_mask:0xf bound_ctrl:1
	v_pk_mul_f32 v[206:207], v[206:207], v[246:247]
	v_fmac_f32_dpp v225, v61, v161 row_ror:1 row_mask:0xf bank_mask:0xf bound_ctrl:1
	v_pk_mul_f32 v[226:227], v[226:227], v[248:249]
	v_fmac_f32_dpp v218, v150, v182 row_ror:2 row_mask:0xf bank_mask:0xf bound_ctrl:1
	v_pk_mul_f32 v[142:143], v[142:143], v[202:203]
	v_fmac_f32_dpp v219, v151, v183 row_ror:2 row_mask:0xf bank_mask:0xf bound_ctrl:1
	v_pk_mul_f32 v[144:145], v[144:145], v[204:205]
	v_fmac_f32_dpp v220, v152, v184 row_ror:2 row_mask:0xf bank_mask:0xf bound_ctrl:1
	v_pk_mul_f32 v[138:139], v[138:139], v[206:207]
	v_fmac_f32_dpp v221, v153, v185 row_ror:2 row_mask:0xf bank_mask:0xf bound_ctrl:1
	v_pk_mul_f32 v[140:141], v[140:141], v[226:227]
	v_fmac_f32_dpp v222, v58, v190 row_ror:2 row_mask:0xf bank_mask:0xf bound_ctrl:1
	v_cvt_pk_bf16_f32 v250, v142, v143
	v_fmac_f32_dpp v223, v59, v191 row_ror:2 row_mask:0xf bank_mask:0xf bound_ctrl:1
	v_cvt_pk_bf16_f32 v251, v144, v145
	v_fmac_f32_dpp v224, v60, v192 row_ror:2 row_mask:0xf bank_mask:0xf bound_ctrl:1
	v_cvt_pk_bf16_f32 v252, v138, v139
	v_fmac_f32_dpp v225, v61, v193 row_ror:2 row_mask:0xf bank_mask:0xf bound_ctrl:1
	v_cvt_pk_bf16_f32 v253, v140, v141
	s_mov_b64 s[76:77], exec
	s_cmp_lg_u32 s15, 0
	s_cbranch_scc1 .Lepi_st00
	s_andn2_b64 s[76:77], exec, s[42:43]
.Lepi_st00:
	s_and_saveexec_b64 s[70:71], s[76:77]
	global_store_dwordx4 v175, v[250:253], s[72:73]
	s_or_b64 exec, exec, s[70:71]
	s_add_u32 s72, s84, 0x16000
	v_pk_mul_f32 v[202:203], v[118:119], v[78:79]
	s_addc_u32 s73, s85, 0
	v_pk_mul_f32 v[204:205], v[120:121], v[80:81]
	v_pk_mul_f32 v[242:243], v[218:219], s[98:99]
	v_pk_mul_f32 v[206:207], v[114:115], v[82:83]
	v_pk_mul_f32 v[244:245], v[220:221], s[98:99]
	v_pk_mul_f32 v[226:227], v[116:117], v[84:85]
	v_pk_mul_f32 v[246:247], v[222:223], s[98:99]
	v_fmac_f32_dpp v202, v118, v26 row_shr:1 row_mask:0xf bank_mask:0xf bound_ctrl:1
	v_pk_mul_f32 v[248:249], v[224:225], s[98:99]
	v_fmac_f32_dpp v203, v119, v27 row_shr:1 row_mask:0xf bank_mask:0xf bound_ctrl:1
	v_exp_f32_e32 v242, v242
	v_fmac_f32_dpp v204, v120, v28 row_shr:1 row_mask:0xf bank_mask:0xf bound_ctrl:1
	v_exp_f32_e32 v243, v243
	v_fmac_f32_dpp v205, v121, v29 row_shr:1 row_mask:0xf bank_mask:0xf bound_ctrl:1
	v_exp_f32_e32 v244, v244
	v_fmac_f32_dpp v206, v114, v74 row_shr:1 row_mask:0xf bank_mask:0xf bound_ctrl:1
	v_exp_f32_e32 v245, v245
	v_fmac_f32_dpp v207, v115, v75 row_shr:1 row_mask:0xf bank_mask:0xf bound_ctrl:1
	v_exp_f32_e32 v246, v246
	v_fmac_f32_dpp v226, v116, v76 row_shr:1 row_mask:0xf bank_mask:0xf bound_ctrl:1
	v_exp_f32_e32 v247, v247
	v_fmac_f32_dpp v227, v117, v77 row_shr:1 row_mask:0xf bank_mask:0xf bound_ctrl:1
	v_exp_f32_e32 v248, v248
	v_fmac_f32_dpp v202, v118, v14 row_shr:2 row_mask:0xf bank_mask:0xf bound_ctrl:1
	v_exp_f32_e32 v249, v249
	v_fmac_f32_dpp v203, v119, v15 row_shr:2 row_mask:0xf bank_mask:0xf bound_ctrl:1
	v_pk_add_f32 v[242:243], v[242:243], s[92:93]
	v_fmac_f32_dpp v204, v120, v16 row_shr:2 row_mask:0xf bank_mask:0xf bound_ctrl:1
	v_pk_add_f32 v[244:245], v[244:245], s[92:93]
	v_fmac_f32_dpp v205, v121, v17 row_shr:2 row_mask:0xf bank_mask:0xf bound_ctrl:1
	v_pk_add_f32 v[246:247], v[246:247], s[92:93]
	v_fmac_f32_dpp v206, v114, v22 row_shr:2 row_mask:0xf bank_mask:0xf bound_ctrl:1
	v_pk_add_f32 v[248:249], v[248:249], s[92:93]
	v_fmac_f32_dpp v207, v115, v23 row_shr:2 row_mask:0xf bank_mask:0xf bound_ctrl:1
	v_rcp_f32_e32 v242, v242
	v_fmac_f32_dpp v226, v116, v24 row_shr:2 row_mask:0xf bank_mask:0xf bound_ctrl:1
	v_rcp_f32_e32 v243, v243
	v_fmac_f32_dpp v227, v117, v25 row_shr:2 row_mask:0xf bank_mask:0xf bound_ctrl:1
	v_rcp_f32_e32 v244, v244
	v_fmac_f32_dpp v202, v126, v154 row_ror:1 row_mask:0xf bank_mask:0xf bound_ctrl:1
	v_rcp_f32_e32 v245, v245
	v_fmac_f32_dpp v203, v127, v155 row_ror:1 row_mask:0xf bank_mask:0xf bound_ctrl:1
	v_rcp_f32_e32 v246, v246
	v_fmac_f32_dpp v204, v128, v156 row_ror:1 row_mask:0xf bank_mask:0xf bound_ctrl:1
	v_rcp_f32_e32 v247, v247
	v_fmac_f32_dpp v205, v129, v157 row_ror:1 row_mask:0xf bank_mask:0xf bound_ctrl:1
	v_rcp_f32_e32 v248, v248
	v_fmac_f32_dpp v206, v122, v158 row_ror:1 row_mask:0xf bank_mask:0xf bound_ctrl:1
	v_rcp_f32_e32 v249, v249
	v_fmac_f32_dpp v207, v123, v159 row_ror:1 row_mask:0xf bank_mask:0xf bound_ctrl:1
	v_pk_mul_f32 v[218:219], v[218:219], v[242:243]
	v_fmac_f32_dpp v226, v124, v160 row_ror:1 row_mask:0xf bank_mask:0xf bound_ctrl:1
	v_pk_mul_f32 v[220:221], v[220:221], v[244:245]
	v_fmac_f32_dpp v227, v125, v161 row_ror:1 row_mask:0xf bank_mask:0xf bound_ctrl:1
	v_pk_mul_f32 v[222:223], v[222:223], v[246:247]
	v_fmac_f32_dpp v202, v126, v182 row_ror:2 row_mask:0xf bank_mask:0xf bound_ctrl:1
	v_pk_mul_f32 v[224:225], v[224:225], v[248:249]
	v_fmac_f32_dpp v203, v127, v183 row_ror:2 row_mask:0xf bank_mask:0xf bound_ctrl:1
	v_pk_mul_f32 v[110:111], v[110:111], v[218:219]
	v_fmac_f32_dpp v204, v128, v184 row_ror:2 row_mask:0xf bank_mask:0xf bound_ctrl:1
	v_pk_mul_f32 v[112:113], v[112:113], v[220:221]
	v_fmac_f32_dpp v205, v129, v185 row_ror:2 row_mask:0xf bank_mask:0xf bound_ctrl:1
	v_pk_mul_f32 v[106:107], v[106:107], v[222:223]
	v_fmac_f32_dpp v206, v122, v190 row_ror:2 row_mask:0xf bank_mask:0xf bound_ctrl:1
	v_pk_mul_f32 v[108:109], v[108:109], v[224:225]
	v_fmac_f32_dpp v207, v123, v191 row_ror:2 row_mask:0xf bank_mask:0xf bound_ctrl:1
	v_cvt_pk_bf16_f32 v250, v110, v111
	v_fmac_f32_dpp v226, v124, v192 row_ror:2 row_mask:0xf bank_mask:0xf bound_ctrl:1
	v_cvt_pk_bf16_f32 v251, v112, v113
	v_fmac_f32_dpp v227, v125, v193 row_ror:2 row_mask:0xf bank_mask:0xf bound_ctrl:1
	v_cvt_pk_bf16_f32 v252, v106, v107
	v_cvt_pk_bf16_f32 v253, v108, v109
	global_store_dwordx4 v175, v[250:253], s[72:73]
	s_add_u32 s72, s84, 0x2c000
	v_pk_mul_f32 v[218:219], v[134:135], v[78:79]
	s_addc_u32 s73, s85, 0
	v_pk_mul_f32 v[220:221], v[136:137], v[80:81]
	v_pk_mul_f32 v[242:243], v[202:203], s[98:99]
	v_pk_mul_f32 v[222:223], v[130:131], v[82:83]
	v_pk_mul_f32 v[244:245], v[204:205], s[98:99]
	v_pk_mul_f32 v[224:225], v[132:133], v[84:85]
	v_pk_mul_f32 v[246:247], v[206:207], s[98:99]
	v_fmac_f32_dpp v218, v134, v26 row_shr:1 row_mask:0xf bank_mask:0xf bound_ctrl:1
	v_pk_mul_f32 v[248:249], v[226:227], s[98:99]
	v_fmac_f32_dpp v219, v135, v27 row_shr:1 row_mask:0xf bank_mask:0xf bound_ctrl:1
	v_exp_f32_e32 v242, v242
	v_fmac_f32_dpp v220, v136, v28 row_shr:1 row_mask:0xf bank_mask:0xf bound_ctrl:1
	v_exp_f32_e32 v243, v243
	v_fmac_f32_dpp v221, v137, v29 row_shr:1 row_mask:0xf bank_mask:0xf bound_ctrl:1
	v_exp_f32_e32 v244, v244
	v_fmac_f32_dpp v222, v130, v74 row_shr:1 row_mask:0xf bank_mask:0xf bound_ctrl:1
	v_exp_f32_e32 v245, v245
	v_fmac_f32_dpp v223, v131, v75 row_shr:1 row_mask:0xf bank_mask:0xf bound_ctrl:1
	v_exp_f32_e32 v246, v246
	v_fmac_f32_dpp v224, v132, v76 row_shr:1 row_mask:0xf bank_mask:0xf bound_ctrl:1
	v_exp_f32_e32 v247, v247
	v_fmac_f32_dpp v225, v133, v77 row_shr:1 row_mask:0xf bank_mask:0xf bound_ctrl:1
	v_exp_f32_e32 v248, v248
	v_fmac_f32_dpp v218, v134, v14 row_shr:2 row_mask:0xf bank_mask:0xf bound_ctrl:1
	v_exp_f32_e32 v249, v249
	v_fmac_f32_dpp v219, v135, v15 row_shr:2 row_mask:0xf bank_mask:0xf bound_ctrl:1
	v_pk_add_f32 v[242:243], v[242:243], s[92:93]
	v_fmac_f32_dpp v220, v136, v16 row_shr:2 row_mask:0xf bank_mask:0xf bound_ctrl:1
	v_pk_add_f32 v[244:245], v[244:245], s[92:93]
	v_fmac_f32_dpp v221, v137, v17 row_shr:2 row_mask:0xf bank_mask:0xf bound_ctrl:1
	v_pk_add_f32 v[246:247], v[246:247], s[92:93]
	v_fmac_f32_dpp v222, v130, v22 row_shr:2 row_mask:0xf bank_mask:0xf bound_ctrl:1
	v_pk_add_f32 v[248:249], v[248:249], s[92:93]
	v_fmac_f32_dpp v223, v131, v23 row_shr:2 row_mask:0xf bank_mask:0xf bound_ctrl:1
	v_rcp_f32_e32 v242, v242
	v_fmac_f32_dpp v224, v132, v24 row_shr:2 row_mask:0xf bank_mask:0xf bound_ctrl:1
	v_rcp_f32_e32 v243, v243
	v_fmac_f32_dpp v225, v133, v25 row_shr:2 row_mask:0xf bank_mask:0xf bound_ctrl:1
	v_rcp_f32_e32 v244, v244
	v_fmac_f32_dpp v218, v118, v154 row_ror:1 row_mask:0xf bank_mask:0xf bound_ctrl:1
	v_rcp_f32_e32 v245, v245
	v_fmac_f32_dpp v219, v119, v155 row_ror:1 row_mask:0xf bank_mask:0xf bound_ctrl:1
	v_rcp_f32_e32 v246, v246
	v_fmac_f32_dpp v220, v120, v156 row_ror:1 row_mask:0xf bank_mask:0xf bound_ctrl:1
	v_rcp_f32_e32 v247, v247
	v_fmac_f32_dpp v221, v121, v157 row_ror:1 row_mask:0xf bank_mask:0xf bound_ctrl:1
	v_rcp_f32_e32 v248, v248
	v_fmac_f32_dpp v222, v114, v158 row_ror:1 row_mask:0xf bank_mask:0xf bound_ctrl:1
	v_rcp_f32_e32 v249, v249
	v_fmac_f32_dpp v223, v115, v159 row_ror:1 row_mask:0xf bank_mask:0xf bound_ctrl:1
	v_pk_mul_f32 v[202:203], v[202:203], v[242:243]
	v_fmac_f32_dpp v224, v116, v160 row_ror:1 row_mask:0xf bank_mask:0xf bound_ctrl:1
	v_pk_mul_f32 v[204:205], v[204:205], v[244:245]
	v_fmac_f32_dpp v225, v117, v161 row_ror:1 row_mask:0xf bank_mask:0xf bound_ctrl:1
	v_pk_mul_f32 v[206:207], v[206:207], v[246:247]
	v_fmac_f32_dpp v218, v118, v182 row_ror:2 row_mask:0xf bank_mask:0xf bound_ctrl:1
	v_pk_mul_f32 v[226:227], v[226:227], v[248:249]
	v_fmac_f32_dpp v219, v119, v183 row_ror:2 row_mask:0xf bank_mask:0xf bound_ctrl:1
	v_pk_mul_f32 v[102:103], v[102:103], v[202:203]
	v_fmac_f32_dpp v220, v120, v184 row_ror:2 row_mask:0xf bank_mask:0xf bound_ctrl:1
	v_pk_mul_f32 v[104:105], v[104:105], v[204:205]
	v_fmac_f32_dpp v221, v121, v185 row_ror:2 row_mask:0xf bank_mask:0xf bound_ctrl:1
	v_pk_mul_f32 v[98:99], v[98:99], v[206:207]
	v_fmac_f32_dpp v222, v114, v190 row_ror:2 row_mask:0xf bank_mask:0xf bound_ctrl:1
	v_pk_mul_f32 v[100:101], v[100:101], v[226:227]
	v_fmac_f32_dpp v223, v115, v191 row_ror:2 row_mask:0xf bank_mask:0xf bound_ctrl:1
	v_cvt_pk_bf16_f32 v250, v102, v103
	v_fmac_f32_dpp v224, v116, v192 row_ror:2 row_mask:0xf bank_mask:0xf bound_ctrl:1
	v_cvt_pk_bf16_f32 v251, v104, v105
	v_fmac_f32_dpp v225, v117, v193 row_ror:2 row_mask:0xf bank_mask:0xf bound_ctrl:1
	v_cvt_pk_bf16_f32 v252, v98, v99
	v_cvt_pk_bf16_f32 v253, v100, v101
	global_store_dwordx4 v175, v[250:253], s[72:73]
	s_add_u32 s72, s84, 0x42000
	v_pk_mul_f32 v[202:203], v[70:71], v[78:79]
	s_addc_u32 s73, s85, 0
	v_pk_mul_f32 v[204:205], v[72:73], v[80:81]
	v_pk_mul_f32 v[242:243], v[218:219], s[98:99]
	v_pk_mul_f32 v[206:207], v[66:67], v[82:83]
	v_pk_mul_f32 v[244:245], v[220:221], s[98:99]
	v_pk_mul_f32 v[226:227], v[68:69], v[84:85]
	v_pk_mul_f32 v[246:247], v[222:223], s[98:99]
	v_fmac_f32_dpp v202, v70, v26 row_shr:1 row_mask:0xf bank_mask:0xf bound_ctrl:1
	v_pk_mul_f32 v[248:249], v[224:225], s[98:99]
	v_fmac_f32_dpp v203, v71, v27 row_shr:1 row_mask:0xf bank_mask:0xf bound_ctrl:1
	v_exp_f32_e32 v242, v242
	v_fmac_f32_dpp v204, v72, v28 row_shr:1 row_mask:0xf bank_mask:0xf bound_ctrl:1
	v_exp_f32_e32 v243, v243
	v_fmac_f32_dpp v205, v73, v29 row_shr:1 row_mask:0xf bank_mask:0xf bound_ctrl:1
	v_exp_f32_e32 v244, v244
	v_fmac_f32_dpp v206, v66, v74 row_shr:1 row_mask:0xf bank_mask:0xf bound_ctrl:1
	v_exp_f32_e32 v245, v245
	v_fmac_f32_dpp v207, v67, v75 row_shr:1 row_mask:0xf bank_mask:0xf bound_ctrl:1
	v_exp_f32_e32 v246, v246
	v_fmac_f32_dpp v226, v68, v76 row_shr:1 row_mask:0xf bank_mask:0xf bound_ctrl:1
	v_exp_f32_e32 v247, v247
	v_fmac_f32_dpp v227, v69, v77 row_shr:1 row_mask:0xf bank_mask:0xf bound_ctrl:1
	v_exp_f32_e32 v248, v248
	v_fmac_f32_dpp v202, v70, v14 row_shr:2 row_mask:0xf bank_mask:0xf bound_ctrl:1
	v_exp_f32_e32 v249, v249
	v_fmac_f32_dpp v203, v71, v15 row_shr:2 row_mask:0xf bank_mask:0xf bound_ctrl:1
	v_pk_add_f32 v[242:243], v[242:243], s[92:93]
	v_fmac_f32_dpp v204, v72, v16 row_shr:2 row_mask:0xf bank_mask:0xf bound_ctrl:1
	v_pk_add_f32 v[244:245], v[244:245], s[92:93]
	v_fmac_f32_dpp v205, v73, v17 row_shr:2 row_mask:0xf bank_mask:0xf bound_ctrl:1
	v_pk_add_f32 v[246:247], v[246:247], s[92:93]
	v_fmac_f32_dpp v206, v66, v22 row_shr:2 row_mask:0xf bank_mask:0xf bound_ctrl:1
	v_pk_add_f32 v[248:249], v[248:249], s[92:93]
	v_fmac_f32_dpp v207, v67, v23 row_shr:2 row_mask:0xf bank_mask:0xf bound_ctrl:1
	v_rcp_f32_e32 v242, v242
	v_fmac_f32_dpp v226, v68, v24 row_shr:2 row_mask:0xf bank_mask:0xf bound_ctrl:1
	v_rcp_f32_e32 v243, v243
	v_fmac_f32_dpp v227, v69, v25 row_shr:2 row_mask:0xf bank_mask:0xf bound_ctrl:1
	v_rcp_f32_e32 v244, v244
	v_fmac_f32_dpp v202, v210, v154 row_ror:1 row_mask:0xf bank_mask:0xf bound_ctrl:1
	v_rcp_f32_e32 v245, v245
	v_fmac_f32_dpp v203, v211, v155 row_ror:1 row_mask:0xf bank_mask:0xf bound_ctrl:1
	v_rcp_f32_e32 v246, v246
	v_fmac_f32_dpp v204, v212, v156 row_ror:1 row_mask:0xf bank_mask:0xf bound_ctrl:1
	v_rcp_f32_e32 v247, v247
	v_fmac_f32_dpp v205, v213, v157 row_ror:1 row_mask:0xf bank_mask:0xf bound_ctrl:1
	v_rcp_f32_e32 v248, v248
	v_fmac_f32_dpp v206, v214, v158 row_ror:1 row_mask:0xf bank_mask:0xf bound_ctrl:1
	v_rcp_f32_e32 v249, v249
	v_fmac_f32_dpp v207, v215, v159 row_ror:1 row_mask:0xf bank_mask:0xf bound_ctrl:1
	v_pk_mul_f32 v[218:219], v[218:219], v[242:243]
	v_fmac_f32_dpp v226, v216, v160 row_ror:1 row_mask:0xf bank_mask:0xf bound_ctrl:1
	v_pk_mul_f32 v[220:221], v[220:221], v[244:245]
	v_fmac_f32_dpp v227, v217, v161 row_ror:1 row_mask:0xf bank_mask:0xf bound_ctrl:1
	v_pk_mul_f32 v[222:223], v[222:223], v[246:247]
	v_fmac_f32_dpp v202, v210, v182 row_ror:2 row_mask:0xf bank_mask:0xf bound_ctrl:1
	v_pk_mul_f32 v[224:225], v[224:225], v[248:249]
	v_fmac_f32_dpp v203, v211, v183 row_ror:2 row_mask:0xf bank_mask:0xf bound_ctrl:1
	v_pk_mul_f32 v[94:95], v[94:95], v[218:219]
	v_fmac_f32_dpp v204, v212, v184 row_ror:2 row_mask:0xf bank_mask:0xf bound_ctrl:1
	v_pk_mul_f32 v[96:97], v[96:97], v[220:221]
	v_fmac_f32_dpp v205, v213, v185 row_ror:2 row_mask:0xf bank_mask:0xf bound_ctrl:1
	v_pk_mul_f32 v[90:91], v[90:91], v[222:223]
	v_fmac_f32_dpp v206, v214, v190 row_ror:2 row_mask:0xf bank_mask:0xf bound_ctrl:1
	v_pk_mul_f32 v[92:93], v[92:93], v[224:225]
	v_fmac_f32_dpp v207, v215, v191 row_ror:2 row_mask:0xf bank_mask:0xf bound_ctrl:1
	v_cvt_pk_bf16_f32 v250, v94, v95
	v_fmac_f32_dpp v226, v216, v192 row_ror:2 row_mask:0xf bank_mask:0xf bound_ctrl:1
	v_cvt_pk_bf16_f32 v251, v96, v97
	v_fmac_f32_dpp v227, v217, v193 row_ror:2 row_mask:0xf bank_mask:0xf bound_ctrl:1
	v_cvt_pk_bf16_f32 v252, v90, v91
	v_cvt_pk_bf16_f32 v253, v92, v93
	global_store_dwordx4 v175, v[250:253], s[72:73]
	s_add_u32 s72, s84, 0xb0000
	v_pk_mul_f32 v[218:219], v[62:63], v[78:79]
	s_addc_u32 s73, s85, 0
	v_pk_mul_f32 v[220:221], v[64:65], v[80:81]
	v_pk_mul_f32 v[242:243], v[202:203], s[98:99]
	v_pk_mul_f32 v[222:223], v[54:55], v[82:83]
	v_pk_mul_f32 v[244:245], v[204:205], s[98:99]
	v_pk_mul_f32 v[224:225], v[56:57], v[84:85]
	v_pk_mul_f32 v[246:247], v[206:207], s[98:99]
	v_fmac_f32_dpp v218, v62, v26 row_shr:1 row_mask:0xf bank_mask:0xf bound_ctrl:1
	v_pk_mul_f32 v[248:249], v[226:227], s[98:99]
	v_fmac_f32_dpp v219, v63, v27 row_shr:1 row_mask:0xf bank_mask:0xf bound_ctrl:1
	v_exp_f32_e32 v242, v242
	v_fmac_f32_dpp v220, v64, v28 row_shr:1 row_mask:0xf bank_mask:0xf bound_ctrl:1
	v_exp_f32_e32 v243, v243
	v_fmac_f32_dpp v221, v65, v29 row_shr:1 row_mask:0xf bank_mask:0xf bound_ctrl:1
	v_exp_f32_e32 v244, v244
	v_fmac_f32_dpp v222, v54, v74 row_shr:1 row_mask:0xf bank_mask:0xf bound_ctrl:1
	v_exp_f32_e32 v245, v245
	v_fmac_f32_dpp v223, v55, v75 row_shr:1 row_mask:0xf bank_mask:0xf bound_ctrl:1
	v_exp_f32_e32 v246, v246
	v_fmac_f32_dpp v224, v56, v76 row_shr:1 row_mask:0xf bank_mask:0xf bound_ctrl:1
	v_exp_f32_e32 v247, v247
	v_fmac_f32_dpp v225, v57, v77 row_shr:1 row_mask:0xf bank_mask:0xf bound_ctrl:1
	v_exp_f32_e32 v248, v248
	v_fmac_f32_dpp v218, v62, v14 row_shr:2 row_mask:0xf bank_mask:0xf bound_ctrl:1
	v_exp_f32_e32 v249, v249
	v_fmac_f32_dpp v219, v63, v15 row_shr:2 row_mask:0xf bank_mask:0xf bound_ctrl:1
	v_pk_add_f32 v[242:243], v[242:243], s[92:93]
	v_fmac_f32_dpp v220, v64, v16 row_shr:2 row_mask:0xf bank_mask:0xf bound_ctrl:1
	v_pk_add_f32 v[244:245], v[244:245], s[92:93]
	v_fmac_f32_dpp v221, v65, v17 row_shr:2 row_mask:0xf bank_mask:0xf bound_ctrl:1
	v_pk_add_f32 v[246:247], v[246:247], s[92:93]
	v_fmac_f32_dpp v222, v54, v22 row_shr:2 row_mask:0xf bank_mask:0xf bound_ctrl:1
	v_pk_add_f32 v[248:249], v[248:249], s[92:93]
	v_fmac_f32_dpp v223, v55, v23 row_shr:2 row_mask:0xf bank_mask:0xf bound_ctrl:1
	v_rcp_f32_e32 v242, v242
	v_fmac_f32_dpp v224, v56, v24 row_shr:2 row_mask:0xf bank_mask:0xf bound_ctrl:1
	v_rcp_f32_e32 v243, v243
	v_fmac_f32_dpp v225, v57, v25 row_shr:2 row_mask:0xf bank_mask:0xf bound_ctrl:1
	v_rcp_f32_e32 v244, v244
	v_fmac_f32_dpp v218, v70, v154 row_ror:1 row_mask:0xf bank_mask:0xf bound_ctrl:1
	v_rcp_f32_e32 v245, v245
	v_fmac_f32_dpp v219, v71, v155 row_ror:1 row_mask:0xf bank_mask:0xf bound_ctrl:1
	v_rcp_f32_e32 v246, v246
	v_fmac_f32_dpp v220, v72, v156 row_ror:1 row_mask:0xf bank_mask:0xf bound_ctrl:1
	v_rcp_f32_e32 v247, v247
	v_fmac_f32_dpp v221, v73, v157 row_ror:1 row_mask:0xf bank_mask:0xf bound_ctrl:1
	v_rcp_f32_e32 v248, v248
	v_fmac_f32_dpp v222, v66, v158 row_ror:1 row_mask:0xf bank_mask:0xf bound_ctrl:1
	v_rcp_f32_e32 v249, v249
	v_fmac_f32_dpp v223, v67, v159 row_ror:1 row_mask:0xf bank_mask:0xf bound_ctrl:1
	v_pk_mul_f32 v[202:203], v[202:203], v[242:243]
	v_fmac_f32_dpp v224, v68, v160 row_ror:1 row_mask:0xf bank_mask:0xf bound_ctrl:1
	v_pk_mul_f32 v[204:205], v[204:205], v[244:245]
	v_fmac_f32_dpp v225, v69, v161 row_ror:1 row_mask:0xf bank_mask:0xf bound_ctrl:1
	v_pk_mul_f32 v[206:207], v[206:207], v[246:247]
	v_fmac_f32_dpp v218, v70, v182 row_ror:2 row_mask:0xf bank_mask:0xf bound_ctrl:1
	v_pk_mul_f32 v[226:227], v[226:227], v[248:249]
	v_fmac_f32_dpp v219, v71, v183 row_ror:2 row_mask:0xf bank_mask:0xf bound_ctrl:1
	v_pk_mul_f32 v[50:51], v[50:51], v[202:203]
	v_fmac_f32_dpp v220, v72, v184 row_ror:2 row_mask:0xf bank_mask:0xf bound_ctrl:1
	v_pk_mul_f32 v[52:53], v[52:53], v[204:205]
	v_fmac_f32_dpp v221, v73, v185 row_ror:2 row_mask:0xf bank_mask:0xf bound_ctrl:1
	v_pk_mul_f32 v[46:47], v[46:47], v[206:207]
	v_fmac_f32_dpp v222, v66, v190 row_ror:2 row_mask:0xf bank_mask:0xf bound_ctrl:1
	v_pk_mul_f32 v[48:49], v[48:49], v[226:227]
	v_fmac_f32_dpp v223, v67, v191 row_ror:2 row_mask:0xf bank_mask:0xf bound_ctrl:1
	v_cvt_pk_bf16_f32 v250, v50, v51
	v_fmac_f32_dpp v224, v68, v192 row_ror:2 row_mask:0xf bank_mask:0xf bound_ctrl:1
	v_cvt_pk_bf16_f32 v251, v52, v53
	v_fmac_f32_dpp v225, v69, v193 row_ror:2 row_mask:0xf bank_mask:0xf bound_ctrl:1
	v_cvt_pk_bf16_f32 v252, v46, v47
	v_cvt_pk_bf16_f32 v253, v48, v49
	global_store_dwordx4 v175, v[250:253], s[72:73]
	s_add_u32 s72, s84, 0xc6000
	v_pk_mul_f32 v[202:203], v[42:43], v[78:79]
	s_addc_u32 s73, s85, 0
	v_pk_mul_f32 v[204:205], v[44:45], v[80:81]
	v_pk_mul_f32 v[242:243], v[218:219], s[98:99]
	v_pk_mul_f32 v[206:207], v[38:39], v[82:83]
	v_pk_mul_f32 v[244:245], v[220:221], s[98:99]
	v_pk_mul_f32 v[226:227], v[40:41], v[84:85]
	v_pk_mul_f32 v[246:247], v[222:223], s[98:99]
	v_fmac_f32_dpp v202, v42, v26 row_shr:1 row_mask:0xf bank_mask:0xf bound_ctrl:1
	v_pk_mul_f32 v[248:249], v[224:225], s[98:99]
	v_fmac_f32_dpp v203, v43, v27 row_shr:1 row_mask:0xf bank_mask:0xf bound_ctrl:1
	v_exp_f32_e32 v242, v242
	v_fmac_f32_dpp v204, v44, v28 row_shr:1 row_mask:0xf bank_mask:0xf bound_ctrl:1
	v_exp_f32_e32 v243, v243
	v_fmac_f32_dpp v205, v45, v29 row_shr:1 row_mask:0xf bank_mask:0xf bound_ctrl:1
	v_exp_f32_e32 v244, v244
	v_fmac_f32_dpp v206, v38, v74 row_shr:1 row_mask:0xf bank_mask:0xf bound_ctrl:1
	v_exp_f32_e32 v245, v245
	v_fmac_f32_dpp v207, v39, v75 row_shr:1 row_mask:0xf bank_mask:0xf bound_ctrl:1
	v_exp_f32_e32 v246, v246
	v_fmac_f32_dpp v226, v40, v76 row_shr:1 row_mask:0xf bank_mask:0xf bound_ctrl:1
	v_exp_f32_e32 v247, v247
	v_fmac_f32_dpp v227, v41, v77 row_shr:1 row_mask:0xf bank_mask:0xf bound_ctrl:1
	v_exp_f32_e32 v248, v248
	v_fmac_f32_dpp v202, v42, v14 row_shr:2 row_mask:0xf bank_mask:0xf bound_ctrl:1
	v_exp_f32_e32 v249, v249
	v_fmac_f32_dpp v203, v43, v15 row_shr:2 row_mask:0xf bank_mask:0xf bound_ctrl:1
	v_pk_add_f32 v[242:243], v[242:243], s[92:93]
	v_fmac_f32_dpp v204, v44, v16 row_shr:2 row_mask:0xf bank_mask:0xf bound_ctrl:1
	v_pk_add_f32 v[244:245], v[244:245], s[92:93]
	v_fmac_f32_dpp v205, v45, v17 row_shr:2 row_mask:0xf bank_mask:0xf bound_ctrl:1
	v_pk_add_f32 v[246:247], v[246:247], s[92:93]
	v_fmac_f32_dpp v206, v38, v22 row_shr:2 row_mask:0xf bank_mask:0xf bound_ctrl:1
	v_pk_add_f32 v[248:249], v[248:249], s[92:93]
	v_fmac_f32_dpp v207, v39, v23 row_shr:2 row_mask:0xf bank_mask:0xf bound_ctrl:1
	v_rcp_f32_e32 v242, v242
	v_fmac_f32_dpp v226, v40, v24 row_shr:2 row_mask:0xf bank_mask:0xf bound_ctrl:1
	v_rcp_f32_e32 v243, v243
	v_fmac_f32_dpp v227, v41, v25 row_shr:2 row_mask:0xf bank_mask:0xf bound_ctrl:1
	v_rcp_f32_e32 v244, v244
	v_fmac_f32_dpp v202, v62, v154 row_ror:1 row_mask:0xf bank_mask:0xf bound_ctrl:1
	v_rcp_f32_e32 v245, v245
	v_fmac_f32_dpp v203, v63, v155 row_ror:1 row_mask:0xf bank_mask:0xf bound_ctrl:1
	v_rcp_f32_e32 v246, v246
	v_fmac_f32_dpp v204, v64, v156 row_ror:1 row_mask:0xf bank_mask:0xf bound_ctrl:1
	v_rcp_f32_e32 v247, v247
	v_fmac_f32_dpp v205, v65, v157 row_ror:1 row_mask:0xf bank_mask:0xf bound_ctrl:1
	v_rcp_f32_e32 v248, v248
	v_fmac_f32_dpp v206, v54, v158 row_ror:1 row_mask:0xf bank_mask:0xf bound_ctrl:1
	v_rcp_f32_e32 v249, v249
	v_fmac_f32_dpp v207, v55, v159 row_ror:1 row_mask:0xf bank_mask:0xf bound_ctrl:1
	v_pk_mul_f32 v[218:219], v[218:219], v[242:243]
	v_fmac_f32_dpp v226, v56, v160 row_ror:1 row_mask:0xf bank_mask:0xf bound_ctrl:1
	v_pk_mul_f32 v[220:221], v[220:221], v[244:245]
	v_fmac_f32_dpp v227, v57, v161 row_ror:1 row_mask:0xf bank_mask:0xf bound_ctrl:1
	v_pk_mul_f32 v[222:223], v[222:223], v[246:247]
	v_fmac_f32_dpp v202, v62, v182 row_ror:2 row_mask:0xf bank_mask:0xf bound_ctrl:1
	v_pk_mul_f32 v[224:225], v[224:225], v[248:249]
	v_fmac_f32_dpp v203, v63, v183 row_ror:2 row_mask:0xf bank_mask:0xf bound_ctrl:1
	v_pk_mul_f32 v[34:35], v[34:35], v[218:219]
	v_fmac_f32_dpp v204, v64, v184 row_ror:2 row_mask:0xf bank_mask:0xf bound_ctrl:1
	v_pk_mul_f32 v[36:37], v[36:37], v[220:221]
	v_fmac_f32_dpp v205, v65, v185 row_ror:2 row_mask:0xf bank_mask:0xf bound_ctrl:1
	v_pk_mul_f32 v[30:31], v[30:31], v[222:223]
	v_fmac_f32_dpp v206, v54, v190 row_ror:2 row_mask:0xf bank_mask:0xf bound_ctrl:1
	v_pk_mul_f32 v[32:33], v[32:33], v[224:225]
	v_fmac_f32_dpp v207, v55, v191 row_ror:2 row_mask:0xf bank_mask:0xf bound_ctrl:1
	v_cvt_pk_bf16_f32 v250, v34, v35
	v_fmac_f32_dpp v226, v56, v192 row_ror:2 row_mask:0xf bank_mask:0xf bound_ctrl:1
	v_cvt_pk_bf16_f32 v251, v36, v37
	v_fmac_f32_dpp v227, v57, v193 row_ror:2 row_mask:0xf bank_mask:0xf bound_ctrl:1
	v_cvt_pk_bf16_f32 v252, v30, v31
	v_cvt_pk_bf16_f32 v253, v32, v33
	global_store_dwordx4 v175, v[250:253], s[72:73]
	s_add_u32 s72, s84, 0xdc000
	v_pk_mul_f32 v[218:219], v[86:87], v[78:79]
	s_addc_u32 s73, s85, 0
	v_pk_mul_f32 v[220:221], v[88:89], v[80:81]
	v_pk_mul_f32 v[242:243], v[202:203], s[98:99]
	v_pk_mul_f32 v[222:223], v[146:147], v[82:83]
	v_pk_mul_f32 v[244:245], v[204:205], s[98:99]
	v_pk_mul_f32 v[224:225], v[148:149], v[84:85]
	v_pk_mul_f32 v[246:247], v[206:207], s[98:99]
	v_fmac_f32_dpp v218, v86, v26 row_shr:1 row_mask:0xf bank_mask:0xf bound_ctrl:1
	v_pk_mul_f32 v[248:249], v[226:227], s[98:99]
	v_fmac_f32_dpp v219, v87, v27 row_shr:1 row_mask:0xf bank_mask:0xf bound_ctrl:1
	v_exp_f32_e32 v242, v242
	v_fmac_f32_dpp v220, v88, v28 row_shr:1 row_mask:0xf bank_mask:0xf bound_ctrl:1
	v_exp_f32_e32 v243, v243
	v_fmac_f32_dpp v221, v89, v29 row_shr:1 row_mask:0xf bank_mask:0xf bound_ctrl:1
	v_exp_f32_e32 v244, v244
	v_fmac_f32_dpp v222, v146, v74 row_shr:1 row_mask:0xf bank_mask:0xf bound_ctrl:1
	v_exp_f32_e32 v245, v245
	v_fmac_f32_dpp v223, v147, v75 row_shr:1 row_mask:0xf bank_mask:0xf bound_ctrl:1
	v_exp_f32_e32 v246, v246
	v_fmac_f32_dpp v224, v148, v76 row_shr:1 row_mask:0xf bank_mask:0xf bound_ctrl:1
	v_exp_f32_e32 v247, v247
	v_fmac_f32_dpp v225, v149, v77 row_shr:1 row_mask:0xf bank_mask:0xf bound_ctrl:1
	v_exp_f32_e32 v248, v248
	v_fmac_f32_dpp v218, v86, v14 row_shr:2 row_mask:0xf bank_mask:0xf bound_ctrl:1
	v_exp_f32_e32 v249, v249
	v_fmac_f32_dpp v219, v87, v15 row_shr:2 row_mask:0xf bank_mask:0xf bound_ctrl:1
	v_pk_add_f32 v[242:243], v[242:243], s[92:93]
	v_fmac_f32_dpp v220, v88, v16 row_shr:2 row_mask:0xf bank_mask:0xf bound_ctrl:1
	v_pk_add_f32 v[244:245], v[244:245], s[92:93]
	v_fmac_f32_dpp v221, v89, v17 row_shr:2 row_mask:0xf bank_mask:0xf bound_ctrl:1
	v_pk_add_f32 v[246:247], v[246:247], s[92:93]
	v_fmac_f32_dpp v222, v146, v22 row_shr:2 row_mask:0xf bank_mask:0xf bound_ctrl:1
	v_pk_add_f32 v[248:249], v[248:249], s[92:93]
	v_fmac_f32_dpp v223, v147, v23 row_shr:2 row_mask:0xf bank_mask:0xf bound_ctrl:1
	v_rcp_f32_e32 v242, v242
	v_fmac_f32_dpp v224, v148, v24 row_shr:2 row_mask:0xf bank_mask:0xf bound_ctrl:1
	v_rcp_f32_e32 v243, v243
	v_fmac_f32_dpp v225, v149, v25 row_shr:2 row_mask:0xf bank_mask:0xf bound_ctrl:1
	v_rcp_f32_e32 v244, v244
	v_fmac_f32_dpp v218, v42, v154 row_ror:1 row_mask:0xf bank_mask:0xf bound_ctrl:1
	v_rcp_f32_e32 v245, v245
	v_fmac_f32_dpp v219, v43, v155 row_ror:1 row_mask:0xf bank_mask:0xf bound_ctrl:1
	v_rcp_f32_e32 v246, v246
	v_fmac_f32_dpp v220, v44, v156 row_ror:1 row_mask:0xf bank_mask:0xf bound_ctrl:1
	v_rcp_f32_e32 v247, v247
	v_fmac_f32_dpp v221, v45, v157 row_ror:1 row_mask:0xf bank_mask:0xf bound_ctrl:1
	v_rcp_f32_e32 v248, v248
	v_fmac_f32_dpp v222, v38, v158 row_ror:1 row_mask:0xf bank_mask:0xf bound_ctrl:1
	v_rcp_f32_e32 v249, v249
	v_fmac_f32_dpp v223, v39, v159 row_ror:1 row_mask:0xf bank_mask:0xf bound_ctrl:1
	v_pk_mul_f32 v[202:203], v[202:203], v[242:243]
	v_fmac_f32_dpp v224, v40, v160 row_ror:1 row_mask:0xf bank_mask:0xf bound_ctrl:1
	v_pk_mul_f32 v[204:205], v[204:205], v[244:245]
	v_fmac_f32_dpp v225, v41, v161 row_ror:1 row_mask:0xf bank_mask:0xf bound_ctrl:1
	v_pk_mul_f32 v[206:207], v[206:207], v[246:247]
	v_fmac_f32_dpp v218, v42, v182 row_ror:2 row_mask:0xf bank_mask:0xf bound_ctrl:1
	v_pk_mul_f32 v[226:227], v[226:227], v[248:249]
	v_fmac_f32_dpp v219, v43, v183 row_ror:2 row_mask:0xf bank_mask:0xf bound_ctrl:1
	v_pk_mul_f32 v[18:19], v[18:19], v[202:203]
	v_fmac_f32_dpp v220, v44, v184 row_ror:2 row_mask:0xf bank_mask:0xf bound_ctrl:1
	v_pk_mul_f32 v[20:21], v[20:21], v[204:205]
	v_fmac_f32_dpp v221, v45, v185 row_ror:2 row_mask:0xf bank_mask:0xf bound_ctrl:1
	v_pk_mul_f32 v[10:11], v[10:11], v[206:207]
	v_fmac_f32_dpp v222, v38, v190 row_ror:2 row_mask:0xf bank_mask:0xf bound_ctrl:1
	v_pk_mul_f32 v[12:13], v[12:13], v[226:227]
	v_fmac_f32_dpp v223, v39, v191 row_ror:2 row_mask:0xf bank_mask:0xf bound_ctrl:1
	v_cvt_pk_bf16_f32 v250, v18, v19
	v_fmac_f32_dpp v224, v40, v192 row_ror:2 row_mask:0xf bank_mask:0xf bound_ctrl:1
	v_cvt_pk_bf16_f32 v251, v20, v21
	v_fmac_f32_dpp v225, v41, v193 row_ror:2 row_mask:0xf bank_mask:0xf bound_ctrl:1
	v_cvt_pk_bf16_f32 v252, v10, v11
	v_cvt_pk_bf16_f32 v253, v12, v13
	global_store_dwordx4 v175, v[250:253], s[72:73]
	s_add_u32 s72, s84, 0xf2000
	s_addc_u32 s73, s85, 0
	v_pk_mul_f32 v[242:243], v[218:219], s[98:99]
	v_pk_mul_f32 v[244:245], v[220:221], s[98:99]
	v_pk_mul_f32 v[246:247], v[222:223], s[98:99]
	v_pk_mul_f32 v[248:249], v[224:225], s[98:99]
	v_exp_f32_e32 v242, v242
	v_exp_f32_e32 v243, v243
	v_exp_f32_e32 v244, v244
	v_exp_f32_e32 v245, v245
	v_exp_f32_e32 v246, v246
	v_exp_f32_e32 v247, v247
	v_exp_f32_e32 v248, v248
	v_exp_f32_e32 v249, v249
	v_pk_add_f32 v[242:243], v[242:243], s[92:93]
	v_pk_add_f32 v[244:245], v[244:245], s[92:93]
	v_pk_add_f32 v[246:247], v[246:247], s[92:93]
	v_pk_add_f32 v[248:249], v[248:249], s[92:93]
	v_rcp_f32_e32 v242, v242
	v_rcp_f32_e32 v243, v243
	v_rcp_f32_e32 v244, v244
	v_rcp_f32_e32 v245, v245
	v_rcp_f32_e32 v246, v246
	v_rcp_f32_e32 v247, v247
	v_rcp_f32_e32 v248, v248
	v_rcp_f32_e32 v249, v249
	v_pk_mul_f32 v[218:219], v[218:219], v[242:243]
	v_pk_mul_f32 v[220:221], v[220:221], v[244:245]
	v_pk_mul_f32 v[222:223], v[222:223], v[246:247]
	v_pk_mul_f32 v[224:225], v[224:225], v[248:249]
	v_pk_mul_f32 v[6:7], v[6:7], v[218:219]
	v_pk_mul_f32 v[8:9], v[8:9], v[220:221]
	v_pk_mul_f32 v[2:3], v[2:3], v[222:223]
	v_pk_mul_f32 v[4:5], v[4:5], v[224:225]
	v_cvt_pk_bf16_f32 v250, v6, v7
	v_cvt_pk_bf16_f32 v251, v8, v9
	v_cvt_pk_bf16_f32 v252, v2, v3
	v_cvt_pk_bf16_f32 v253, v4, v5
	global_store_dwordx4 v175, v[250:253], s[72:73]
	s_andn2_b64 vcc, exec, s[38:39]
	s_mov_b64 s[38:39], -1
	s_cbranch_vccnz .LBB0_239
	s_andn2_b64 vcc, exec, s[62:63]
	s_cbranch_vccnz .LBB0_238
	s_barrier
	s_branch .LBB0_238
